# G1 SwiGLU epilogue math packed: v_pk_mul/v_pk_add f32 pairs (same f32 ops, bitwise identical)
# baseline (speedup 1.0000x reference)
.LBB0_1108:
	v_mov_b32_e32 v174, 0xbfb8aa3b
	v_mov_b32_e32 v175, 0xbfb8aa3b
	v_pk_mul_f32 v[152:153], v[126:127], v[174:175]
	v_pk_mul_f32 v[154:155], v[128:129], v[174:175]
	v_pk_mul_f32 v[156:157], v[118:119], v[174:175]
	v_pk_mul_f32 v[158:159], v[120:121], v[174:175]
	v_exp_f32_e32 v152, v152
	v_exp_f32_e32 v153, v153
	v_exp_f32_e32 v154, v154
	v_exp_f32_e32 v155, v155
	v_exp_f32_e32 v156, v156
	v_exp_f32_e32 v157, v157
	v_exp_f32_e32 v158, v158
	v_exp_f32_e32 v159, v159
	v_pk_add_f32 v[152:153], v[152:153], 1.0 op_sel_hi:[1,0]
	v_pk_add_f32 v[154:155], v[154:155], 1.0 op_sel_hi:[1,0]
	v_pk_add_f32 v[156:157], v[156:157], 1.0 op_sel_hi:[1,0]
	v_pk_add_f32 v[158:159], v[158:159], 1.0 op_sel_hi:[1,0]
	v_rcp_f32_e32 v152, v152
	v_rcp_f32_e32 v153, v153
	v_rcp_f32_e32 v154, v154
	v_rcp_f32_e32 v155, v155
	v_rcp_f32_e32 v156, v156
	v_rcp_f32_e32 v157, v157
	v_rcp_f32_e32 v158, v158
	v_rcp_f32_e32 v159, v159
	v_pk_mul_f32 v[152:153], v[126:127], v[152:153]
	v_pk_mul_f32 v[154:155], v[128:129], v[154:155]
	v_pk_mul_f32 v[156:157], v[118:119], v[156:157]
	v_pk_mul_f32 v[158:159], v[120:121], v[158:159]
	v_pk_mul_f32 v[152:153], v[152:153], v[122:123]
	v_pk_mul_f32 v[154:155], v[154:155], v[124:125]
	v_pk_mul_f32 v[156:157], v[156:157], v[114:115]
	v_pk_mul_f32 v[158:159], v[158:159], v[116:117]
	s_nop 0
	v_cvt_pk_bf16_f32 v168, v152, v153
	v_cvt_pk_bf16_f32 v169, v154, v155
	v_cvt_pk_bf16_f32 v170, v156, v157
	v_cvt_pk_bf16_f32 v171, v158, v159
	v_lshl_add_u32 v148, s28, 7, v144
	v_lshl_add_u32 v146, s86, 8, v142
	v_ashrrev_i32_e32 v149, 31, v148
	v_mov_b64_e32 v[140:141], s[8:9]
	v_mad_i64_i32 v[150:151], s[28:29], v146, s73, v[140:141]
	s_andn2_b64 vcc, exec, s[4:5]
	v_lshlrev_b64 v[114:115], 1, v[148:149]
	v_lshl_add_u64 v[120:121], v[150:151], 0, v[114:115]
	global_store_dwordx4 v[120:121], v[168:171], off
	v_pk_mul_f32 v[152:153], v[110:111], v[174:175]
	v_pk_mul_f32 v[154:155], v[112:113], v[174:175]
	v_pk_mul_f32 v[156:157], v[102:103], v[174:175]
	v_pk_mul_f32 v[158:159], v[104:105], v[174:175]
	v_exp_f32_e32 v152, v152
	v_exp_f32_e32 v153, v153
	v_exp_f32_e32 v154, v154
	v_exp_f32_e32 v155, v155
	v_exp_f32_e32 v156, v156
	v_exp_f32_e32 v157, v157
	v_exp_f32_e32 v158, v158
	v_exp_f32_e32 v159, v159
	v_pk_add_f32 v[152:153], v[152:153], 1.0 op_sel_hi:[1,0]
	v_pk_add_f32 v[154:155], v[154:155], 1.0 op_sel_hi:[1,0]
	v_pk_add_f32 v[156:157], v[156:157], 1.0 op_sel_hi:[1,0]
	v_pk_add_f32 v[158:159], v[158:159], 1.0 op_sel_hi:[1,0]
	v_rcp_f32_e32 v152, v152
	v_rcp_f32_e32 v153, v153
	v_rcp_f32_e32 v154, v154
	v_rcp_f32_e32 v155, v155
	v_rcp_f32_e32 v156, v156
	v_rcp_f32_e32 v157, v157
	v_rcp_f32_e32 v158, v158
	v_rcp_f32_e32 v159, v159
	v_pk_mul_f32 v[152:153], v[110:111], v[152:153]
	v_pk_mul_f32 v[154:155], v[112:113], v[154:155]
	v_pk_mul_f32 v[156:157], v[102:103], v[156:157]
	v_pk_mul_f32 v[158:159], v[104:105], v[158:159]
	v_pk_mul_f32 v[152:153], v[152:153], v[106:107]
	v_pk_mul_f32 v[154:155], v[154:155], v[108:109]
	v_pk_mul_f32 v[156:157], v[156:157], v[98:99]
	v_pk_mul_f32 v[158:159], v[158:159], v[100:101]
	s_nop 0
	v_cvt_pk_bf16_f32 v168, v152, v153
	v_cvt_pk_bf16_f32 v169, v154, v155
	v_cvt_pk_bf16_f32 v170, v156, v157
	v_cvt_pk_bf16_f32 v171, v158, v159
	v_or_b32_e32 v116, 16, v146
	v_mad_i64_i32 v[116:117], s[28:29], v116, s73, v[140:141]
	v_lshl_add_u64 v[102:103], v[116:117], 0, v[114:115]
	global_store_dwordx4 v[102:103], v[168:171], off
	v_pk_mul_f32 v[152:153], v[94:95], v[174:175]
	v_pk_mul_f32 v[154:155], v[96:97], v[174:175]
	v_pk_mul_f32 v[156:157], v[86:87], v[174:175]
	v_pk_mul_f32 v[158:159], v[88:89], v[174:175]
	v_exp_f32_e32 v152, v152
	v_exp_f32_e32 v153, v153
	v_exp_f32_e32 v154, v154
	v_exp_f32_e32 v155, v155
	v_exp_f32_e32 v156, v156
	v_exp_f32_e32 v157, v157
	v_exp_f32_e32 v158, v158
	v_exp_f32_e32 v159, v159
	v_pk_add_f32 v[152:153], v[152:153], 1.0 op_sel_hi:[1,0]
	v_pk_add_f32 v[154:155], v[154:155], 1.0 op_sel_hi:[1,0]
	v_pk_add_f32 v[156:157], v[156:157], 1.0 op_sel_hi:[1,0]
	v_pk_add_f32 v[158:159], v[158:159], 1.0 op_sel_hi:[1,0]
	v_rcp_f32_e32 v152, v152
	v_rcp_f32_e32 v153, v153
	v_rcp_f32_e32 v154, v154
	v_rcp_f32_e32 v155, v155
	v_rcp_f32_e32 v156, v156
	v_rcp_f32_e32 v157, v157
	v_rcp_f32_e32 v158, v158
	v_rcp_f32_e32 v159, v159
	v_pk_mul_f32 v[152:153], v[94:95], v[152:153]
	v_pk_mul_f32 v[154:155], v[96:97], v[154:155]
	v_pk_mul_f32 v[156:157], v[86:87], v[156:157]
	v_pk_mul_f32 v[158:159], v[88:89], v[158:159]
	v_pk_mul_f32 v[152:153], v[152:153], v[90:91]
	v_pk_mul_f32 v[154:155], v[154:155], v[92:93]
	v_pk_mul_f32 v[156:157], v[156:157], v[82:83]
	v_pk_mul_f32 v[158:159], v[158:159], v[84:85]
	s_nop 0
	v_cvt_pk_bf16_f32 v168, v152, v153
	v_cvt_pk_bf16_f32 v169, v154, v155
	v_cvt_pk_bf16_f32 v170, v156, v157
	v_cvt_pk_bf16_f32 v171, v158, v159
	v_or_b32_e32 v98, 32, v146
	v_mad_i64_i32 v[98:99], s[28:29], v98, s73, v[140:141]
	v_lshl_add_u64 v[86:87], v[98:99], 0, v[114:115]
	global_store_dwordx4 v[86:87], v[168:171], off
	v_pk_mul_f32 v[152:153], v[78:79], v[174:175]
	v_pk_mul_f32 v[154:155], v[80:81], v[174:175]
	v_pk_mul_f32 v[156:157], v[70:71], v[174:175]
	v_pk_mul_f32 v[158:159], v[72:73], v[174:175]
	v_exp_f32_e32 v152, v152
	v_exp_f32_e32 v153, v153
	v_exp_f32_e32 v154, v154
	v_exp_f32_e32 v155, v155
	v_exp_f32_e32 v156, v156
	v_exp_f32_e32 v157, v157
	v_exp_f32_e32 v158, v158
	v_exp_f32_e32 v159, v159
	v_pk_add_f32 v[152:153], v[152:153], 1.0 op_sel_hi:[1,0]
	v_pk_add_f32 v[154:155], v[154:155], 1.0 op_sel_hi:[1,0]
	v_pk_add_f32 v[156:157], v[156:157], 1.0 op_sel_hi:[1,0]
	v_pk_add_f32 v[158:159], v[158:159], 1.0 op_sel_hi:[1,0]
	v_rcp_f32_e32 v152, v152
	v_rcp_f32_e32 v153, v153
	v_rcp_f32_e32 v154, v154
	v_rcp_f32_e32 v155, v155
	v_rcp_f32_e32 v156, v156
	v_rcp_f32_e32 v157, v157
	v_rcp_f32_e32 v158, v158
	v_rcp_f32_e32 v159, v159
	v_pk_mul_f32 v[152:153], v[78:79], v[152:153]
	v_pk_mul_f32 v[154:155], v[80:81], v[154:155]
	v_pk_mul_f32 v[156:157], v[70:71], v[156:157]
	v_pk_mul_f32 v[158:159], v[72:73], v[158:159]
	v_pk_mul_f32 v[152:153], v[152:153], v[74:75]
	v_pk_mul_f32 v[154:155], v[154:155], v[76:77]
	v_pk_mul_f32 v[156:157], v[156:157], v[66:67]
	v_pk_mul_f32 v[158:159], v[158:159], v[68:69]
	s_nop 0
	v_cvt_pk_bf16_f32 v168, v152, v153
	v_cvt_pk_bf16_f32 v169, v154, v155
	v_cvt_pk_bf16_f32 v170, v156, v157
	v_cvt_pk_bf16_f32 v171, v158, v159
	v_or_b32_e32 v82, 48, v146
	v_mad_i64_i32 v[82:83], s[28:29], v82, s73, v[140:141]
	v_lshl_add_u64 v[70:71], v[82:83], 0, v[114:115]
	global_store_dwordx4 v[70:71], v[168:171], off
	v_pk_mul_f32 v[152:153], v[62:63], v[174:175]
	v_pk_mul_f32 v[154:155], v[64:65], v[174:175]
	v_pk_mul_f32 v[156:157], v[54:55], v[174:175]
	v_pk_mul_f32 v[158:159], v[56:57], v[174:175]
	v_exp_f32_e32 v152, v152
	v_exp_f32_e32 v153, v153
	v_exp_f32_e32 v154, v154
	v_exp_f32_e32 v155, v155
	v_exp_f32_e32 v156, v156
	v_exp_f32_e32 v157, v157
	v_exp_f32_e32 v158, v158
	v_exp_f32_e32 v159, v159
	v_pk_add_f32 v[152:153], v[152:153], 1.0 op_sel_hi:[1,0]
	v_pk_add_f32 v[154:155], v[154:155], 1.0 op_sel_hi:[1,0]
	v_pk_add_f32 v[156:157], v[156:157], 1.0 op_sel_hi:[1,0]
	v_pk_add_f32 v[158:159], v[158:159], 1.0 op_sel_hi:[1,0]
	v_rcp_f32_e32 v152, v152
	v_rcp_f32_e32 v153, v153
	v_rcp_f32_e32 v154, v154
	v_rcp_f32_e32 v155, v155
	v_rcp_f32_e32 v156, v156
	v_rcp_f32_e32 v157, v157
	v_rcp_f32_e32 v158, v158
	v_rcp_f32_e32 v159, v159
	v_pk_mul_f32 v[152:153], v[62:63], v[152:153]
	v_pk_mul_f32 v[154:155], v[64:65], v[154:155]
	v_pk_mul_f32 v[156:157], v[54:55], v[156:157]
	v_pk_mul_f32 v[158:159], v[56:57], v[158:159]
	v_pk_mul_f32 v[152:153], v[152:153], v[58:59]
	v_pk_mul_f32 v[154:155], v[154:155], v[60:61]
	v_pk_mul_f32 v[156:157], v[156:157], v[50:51]
	v_pk_mul_f32 v[158:159], v[158:159], v[52:53]
	s_nop 0
	v_cvt_pk_bf16_f32 v168, v152, v153
	v_cvt_pk_bf16_f32 v169, v154, v155
	v_cvt_pk_bf16_f32 v170, v156, v157
	v_cvt_pk_bf16_f32 v171, v158, v159
	v_add_u32_e32 v66, 0x80, v146
	v_mad_i64_i32 v[66:67], s[28:29], v66, s73, v[140:141]
	v_lshl_add_u64 v[54:55], v[66:67], 0, v[114:115]
	global_store_dwordx4 v[54:55], v[168:171], off
	v_pk_mul_f32 v[152:153], v[46:47], v[174:175]
	v_pk_mul_f32 v[154:155], v[48:49], v[174:175]
	v_pk_mul_f32 v[156:157], v[38:39], v[174:175]
	v_pk_mul_f32 v[158:159], v[40:41], v[174:175]
	v_exp_f32_e32 v152, v152
	v_exp_f32_e32 v153, v153
	v_exp_f32_e32 v154, v154
	v_exp_f32_e32 v155, v155
	v_exp_f32_e32 v156, v156
	v_exp_f32_e32 v157, v157
	v_exp_f32_e32 v158, v158
	v_exp_f32_e32 v159, v159
	v_pk_add_f32 v[152:153], v[152:153], 1.0 op_sel_hi:[1,0]
	v_pk_add_f32 v[154:155], v[154:155], 1.0 op_sel_hi:[1,0]
	v_pk_add_f32 v[156:157], v[156:157], 1.0 op_sel_hi:[1,0]
	v_pk_add_f32 v[158:159], v[158:159], 1.0 op_sel_hi:[1,0]
	v_rcp_f32_e32 v152, v152
	v_rcp_f32_e32 v153, v153
	v_rcp_f32_e32 v154, v154
	v_rcp_f32_e32 v155, v155
	v_rcp_f32_e32 v156, v156
	v_rcp_f32_e32 v157, v157
	v_rcp_f32_e32 v158, v158
	v_rcp_f32_e32 v159, v159
	v_pk_mul_f32 v[152:153], v[46:47], v[152:153]
	v_pk_mul_f32 v[154:155], v[48:49], v[154:155]
	v_pk_mul_f32 v[156:157], v[38:39], v[156:157]
	v_pk_mul_f32 v[158:159], v[40:41], v[158:159]
	v_pk_mul_f32 v[152:153], v[152:153], v[42:43]
	v_pk_mul_f32 v[154:155], v[154:155], v[44:45]
	v_pk_mul_f32 v[156:157], v[156:157], v[34:35]
	v_pk_mul_f32 v[158:159], v[158:159], v[36:37]
	s_nop 0
	v_cvt_pk_bf16_f32 v168, v152, v153
	v_cvt_pk_bf16_f32 v169, v154, v155
	v_cvt_pk_bf16_f32 v170, v156, v157
	v_cvt_pk_bf16_f32 v171, v158, v159
	v_add_u32_e32 v50, 0x90, v146
	v_mad_i64_i32 v[50:51], s[28:29], v50, s73, v[140:141]
	v_lshl_add_u64 v[38:39], v[50:51], 0, v[114:115]
	global_store_dwordx4 v[38:39], v[168:171], off
	v_pk_mul_f32 v[152:153], v[30:31], v[174:175]
	v_pk_mul_f32 v[154:155], v[32:33], v[174:175]
	v_pk_mul_f32 v[156:157], v[22:23], v[174:175]
	v_pk_mul_f32 v[158:159], v[24:25], v[174:175]
	v_exp_f32_e32 v152, v152
	v_exp_f32_e32 v153, v153
	v_exp_f32_e32 v154, v154
	v_exp_f32_e32 v155, v155
	v_exp_f32_e32 v156, v156
	v_exp_f32_e32 v157, v157
	v_exp_f32_e32 v158, v158
	v_exp_f32_e32 v159, v159
	v_pk_add_f32 v[152:153], v[152:153], 1.0 op_sel_hi:[1,0]
	v_pk_add_f32 v[154:155], v[154:155], 1.0 op_sel_hi:[1,0]
	v_pk_add_f32 v[156:157], v[156:157], 1.0 op_sel_hi:[1,0]
	v_pk_add_f32 v[158:159], v[158:159], 1.0 op_sel_hi:[1,0]
	v_rcp_f32_e32 v152, v152
	v_rcp_f32_e32 v153, v153
	v_rcp_f32_e32 v154, v154
	v_rcp_f32_e32 v155, v155
	v_rcp_f32_e32 v156, v156
	v_rcp_f32_e32 v157, v157
	v_rcp_f32_e32 v158, v158
	v_rcp_f32_e32 v159, v159
	v_pk_mul_f32 v[152:153], v[30:31], v[152:153]
	v_pk_mul_f32 v[154:155], v[32:33], v[154:155]
	v_pk_mul_f32 v[156:157], v[22:23], v[156:157]
	v_pk_mul_f32 v[158:159], v[24:25], v[158:159]
	v_pk_mul_f32 v[152:153], v[152:153], v[26:27]
	v_pk_mul_f32 v[154:155], v[154:155], v[28:29]
	v_pk_mul_f32 v[156:157], v[156:157], v[18:19]
	v_pk_mul_f32 v[158:159], v[158:159], v[20:21]
	s_nop 0
	v_cvt_pk_bf16_f32 v168, v152, v153
	v_cvt_pk_bf16_f32 v169, v154, v155
	v_cvt_pk_bf16_f32 v170, v156, v157
	v_cvt_pk_bf16_f32 v171, v158, v159
	v_add_u32_e32 v34, 0xa0, v146
	v_mad_i64_i32 v[34:35], s[28:29], v34, s73, v[140:141]
	v_lshl_add_u64 v[22:23], v[34:35], 0, v[114:115]
	global_store_dwordx4 v[22:23], v[168:171], off
	v_pk_mul_f32 v[152:153], v[14:15], v[174:175]
	v_pk_mul_f32 v[154:155], v[16:17], v[174:175]
	v_pk_mul_f32 v[156:157], v[6:7], v[174:175]
	v_pk_mul_f32 v[158:159], v[8:9], v[174:175]
	v_exp_f32_e32 v152, v152
	v_exp_f32_e32 v153, v153
	v_exp_f32_e32 v154, v154
	v_exp_f32_e32 v155, v155
	v_exp_f32_e32 v156, v156
	v_exp_f32_e32 v157, v157
	v_exp_f32_e32 v158, v158
	v_exp_f32_e32 v159, v159
	v_pk_add_f32 v[152:153], v[152:153], 1.0 op_sel_hi:[1,0]
	v_pk_add_f32 v[154:155], v[154:155], 1.0 op_sel_hi:[1,0]
	v_pk_add_f32 v[156:157], v[156:157], 1.0 op_sel_hi:[1,0]
	v_pk_add_f32 v[158:159], v[158:159], 1.0 op_sel_hi:[1,0]
	v_rcp_f32_e32 v152, v152
	v_rcp_f32_e32 v153, v153
	v_rcp_f32_e32 v154, v154
	v_rcp_f32_e32 v155, v155
	v_rcp_f32_e32 v156, v156
	v_rcp_f32_e32 v157, v157
	v_rcp_f32_e32 v158, v158
	v_rcp_f32_e32 v159, v159
	v_pk_mul_f32 v[152:153], v[14:15], v[152:153]
	v_pk_mul_f32 v[154:155], v[16:17], v[154:155]
	v_pk_mul_f32 v[156:157], v[6:7], v[156:157]
	v_pk_mul_f32 v[158:159], v[8:9], v[158:159]
	v_pk_mul_f32 v[152:153], v[152:153], v[10:11]
	v_pk_mul_f32 v[154:155], v[154:155], v[12:13]
	v_pk_mul_f32 v[156:157], v[156:157], v[2:3]
	v_pk_mul_f32 v[158:159], v[158:159], v[4:5]
	s_nop 0
	v_cvt_pk_bf16_f32 v168, v152, v153
	v_cvt_pk_bf16_f32 v169, v154, v155
	v_cvt_pk_bf16_f32 v170, v156, v157
	v_cvt_pk_bf16_f32 v171, v158, v159
	v_add_u32_e32 v18, 0xb0, v146
	v_mad_i64_i32 v[18:19], s[28:29], v18, s73, v[140:141]
	s_mov_b64 s[28:29], -1
	v_lshl_add_u64 v[6:7], v[18:19], 0, v[114:115]
	global_store_dwordx4 v[6:7], v[168:171], off
	s_cbranch_vccnz .LBB0_1101
	s_andn2_b64 vcc, exec, s[6:7]
	s_cbranch_vccnz .LBB0_1100
	s_barrier
	s_branch .LBB0_1100
